# staging writes moved two MFMA slots earlier (before slot 16 of 20)
# baseline (speedup 1.0000x reference)
.LBB0_548:
	s_cmp_gt_u32 s52, s51
	s_mul_i32 s61, s25, 0x2200
	s_cbranch_scc1 .LBB0_550
	s_and_b32 s42, s52, 2
	s_mulk_i32 s42, 0x3400
	v_add_u32_e32 v0, s42, v160
	v_add_u32_e32 v242, s61, v161
	v_add_u32_e32 v163, 0xe000, v242
	v_add_u32_e32 v242, 0xd000, v242
	ds_read_b128 v[82:85], v0 offset:13312
	ds_read_b128 v[98:101], v0 offset:19968
	ds_read_b128 v[164:167], v0 offset:13344
	ds_read_b128 v[168:171], v0 offset:20000
	ds_read2_b64 v[238:241], v242 offset0:0 offset1:2
	ds_read2_b64 v[234:237], v163 offset0:32 offset1:34
	ds_read_b128 v[172:175], v0 offset:13376
	ds_read_b128 v[176:179], v0 offset:20032
	ds_read_b128 v[180:183], v0 offset:13408
	ds_read_b128 v[184:187], v0 offset:20064
	ds_read_b128 v[188:191], v0 offset:13440
	ds_read_b128 v[192:195], v0 offset:20096
	ds_read_b128 v[196:199], v0 offset:13472
	ds_read_b128 v[220:223], v0 offset:20128
	v_exp_f32_e32 v50, v50
	v_exp_f32_e32 v51, v51
	v_exp_f32_e32 v52, v52
	v_exp_f32_e32 v53, v53
	v_exp_f32_e32 v54, v54
	v_exp_f32_e32 v55, v55
	v_exp_f32_e32 v56, v56
	v_exp_f32_e32 v57, v57
	s_waitcnt lgkmcnt(13)
	v_mfma_f32_32x32x16_bf16 v[82:97], v[82:85], v[122:125], 0
	v_cvt_pk_bf16_f32 v224, v50, v51
	v_cvt_pk_bf16_f32 v225, v52, v53
	v_cvt_pk_bf16_f32 v226, v54, v55
	v_cvt_pk_bf16_f32 v227, v56, v57
	v_exp_f32_e32 v58, v58
	v_add_f32_e32 v200, v50, v51
	s_waitcnt lgkmcnt(12)
	v_mfma_f32_32x32x16_bf16 v[98:113], v[98:101], v[122:125], 0
	v_exp_f32_e32 v59, v59
	v_exp_f32_e32 v60, v60
	v_add_f32_e32 v201, v52, v53
	v_exp_f32_e32 v61, v61
	s_waitcnt lgkmcnt(11)
	v_mfma_f32_32x32x16_bf16 v[82:97], v[164:167], v[126:129], v[82:97]
	v_exp_f32_e32 v62, v62
	v_add_f32_e32 v200, v200, v54
	v_exp_f32_e32 v63, v63
	v_add_f32_e32 v201, v201, v55
	v_exp_f32_e32 v64, v64
	s_waitcnt lgkmcnt(10)
	v_mfma_f32_32x32x16_bf16 v[98:113], v[168:171], v[126:129], v[98:113]
	ds_read2_b64 v[164:167], v242 offset0:4 offset1:6
	ds_read2_b64 v[168:171], v163 offset0:36 offset1:38
	v_add_f32_e32 v200, v200, v56
	v_exp_f32_e32 v65, v65
	v_add_f32_e32 v201, v201, v57
	v_cvt_pk_bf16_f32 v228, v58, v59
	v_cvt_pk_bf16_f32 v229, v60, v61
	s_waitcnt lgkmcnt(11)
	v_mfma_f32_32x32x16_bf16 v[18:33], v[238:241], v[224:227], v[18:33]
	v_cvt_pk_bf16_f32 v230, v62, v63
	v_cvt_pk_bf16_f32 v231, v64, v65
	v_exp_f32_e32 v66, v66
	v_add_f32_e32 v200, v200, v58
	v_exp_f32_e32 v67, v67
	v_add_f32_e32 v201, v201, v59
	s_waitcnt lgkmcnt(10)
	v_mfma_f32_32x32x16_bf16 v[34:49], v[234:237], v[224:227], v[34:49]
	v_exp_f32_e32 v68, v68
	v_add_f32_e32 v200, v200, v60
	v_exp_f32_e32 v69, v69
	v_add_f32_e32 v201, v201, v61
	v_exp_f32_e32 v70, v70
	s_waitcnt lgkmcnt(9)
	v_mfma_f32_32x32x16_bf16 v[82:97], v[172:175], v[134:137], v[82:97]
	v_add_f32_e32 v200, v200, v62
	v_exp_f32_e32 v71, v71
	v_add_f32_e32 v201, v201, v63
	v_exp_f32_e32 v72, v72
	v_add_f32_e32 v200, v200, v64
	s_waitcnt lgkmcnt(8)
	v_mfma_f32_32x32x16_bf16 v[98:113], v[176:179], v[134:137], v[98:113]
	ds_read2_b64 v[172:175], v242 offset0:8 offset1:10
	ds_read2_b64 v[176:179], v163 offset0:40 offset1:42
	v_exp_f32_e32 v73, v73
	v_add_f32_e32 v201, v201, v65
	v_cvt_pk_bf16_f32 v224, v66, v67
	v_cvt_pk_bf16_f32 v225, v68, v69
	v_cvt_pk_bf16_f32 v226, v70, v71
	s_waitcnt lgkmcnt(3)
	v_mfma_f32_32x32x16_bf16 v[18:33], v[164:167], v[228:231], v[18:33]
	v_cvt_pk_bf16_f32 v227, v72, v73
	v_exp_f32_e32 v74, v74
	v_add_f32_e32 v200, v200, v66
	v_exp_f32_e32 v75, v75
	v_add_f32_e32 v201, v201, v67
	s_waitcnt lgkmcnt(2)
	v_mfma_f32_32x32x16_bf16 v[34:49], v[168:171], v[228:231], v[34:49]
	v_exp_f32_e32 v76, v76
	v_add_f32_e32 v200, v200, v68
	v_exp_f32_e32 v77, v77
	v_add_f32_e32 v201, v201, v69
	v_exp_f32_e32 v78, v78
	s_waitcnt lgkmcnt(9)
	v_mfma_f32_32x32x16_bf16 v[82:97], v[180:183], v[138:141], v[82:97]
	v_add_f32_e32 v200, v200, v70
	v_exp_f32_e32 v79, v79
	v_add_f32_e32 v201, v201, v71
	v_exp_f32_e32 v80, v80
	v_add_f32_e32 v200, v200, v72
	s_waitcnt lgkmcnt(8)
	v_mfma_f32_32x32x16_bf16 v[98:113], v[184:187], v[138:141], v[98:113]
	ds_read2_b64 v[180:183], v242 offset0:12 offset1:14
	ds_read2_b64 v[184:187], v163 offset0:44 offset1:46
	v_exp_f32_e32 v81, v81
	v_add_f32_e32 v201, v201, v73
	v_cvt_pk_bf16_f32 v228, v74, v75
	v_cvt_pk_bf16_f32 v229, v76, v77
	v_cvt_pk_bf16_f32 v230, v78, v79
	s_waitcnt lgkmcnt(3)
	v_mfma_f32_32x32x16_bf16 v[18:33], v[172:175], v[224:227], v[18:33]
	v_cvt_pk_bf16_f32 v231, v80, v81
	v_add_f32_e32 v200, v200, v74
	v_add_f32_e32 v201, v201, v75
	v_add_f32_e32 v200, v200, v76
	v_add_f32_e32 v201, v201, v77
	v_add_f32_e32 v200, v200, v78
	v_add_f32_e32 v201, v201, v79
	v_add_f32_e32 v200, v200, v80
	s_waitcnt lgkmcnt(2)
	v_mfma_f32_32x32x16_bf16 v[34:49], v[176:179], v[224:227], v[34:49]
	v_add_f32_e32 v201, v201, v81
	v_add_f32_e32 v200, v200, v201
	v_add_f32_e32 v162, v162, v200
	s_waitcnt lgkmcnt(9)
	v_mfma_f32_32x32x16_bf16 v[82:97], v[188:191], v[142:145], v[82:97]
	s_waitcnt lgkmcnt(0)
	v_cndmask_b32_e64 v0, 0, 1, s[44:45]
	v_cmp_ne_u32_e64 s[42:43], 1, v0
	s_andn2_b64 vcc, exec, s[44:45]
	s_cbranch_vccnz .Lt1a_mid
	s_and_b32 s44, s53, 2
	s_mulk_i32 s44, 0x3400
	s_add_i32 s62, s44, 0
	v_add_u32_e32 v0, s62, v151
	s_waitcnt vmcnt(0)
	ds_write_b128 v0, v[118:121]
	s_and_saveexec_b64 s[44:45], s[40:41]
	v_add_u32_e32 v0, s62, v159
	ds_write_b128 v0, v[6:9]
	s_or_b64 exec, exec, s[44:45]

.Lt1a_end:
	v_mfma_f32_32x32x16_bf16 v[98:113], v[192:195], v[142:145], v[98:113]
	v_mfma_f32_32x32x16_bf16 v[82:97], v[196:199], v[146:149], v[82:97]
	v_mfma_f32_32x32x16_bf16 v[98:113], v[220:223], v[146:149], v[98:113]
	v_mfma_f32_32x32x16_bf16 v[18:33], v[180:183], v[228:231], v[18:33]
	v_mfma_f32_32x32x16_bf16 v[34:49], v[184:187], v[228:231], v[34:49]
	s_branch .LBB0_556

.LBB0_563:
	s_cmp_ge_u32 s52, s51
	s_mul_i32 s58, s25, 0x2200
	s_cbranch_scc1 .LBB0_565
	s_andn2_b32 s52, 2, s52
	s_mulk_i32 s52, 0x3400
	v_add_u32_e32 v0, s52, v160
	v_add_u32_e32 v242, s58, v161
	v_add_u32_e32 v163, 0xe000, v242
	v_add_u32_e32 v242, 0xd000, v242
	ds_read_b128 v[50:53], v0 offset:0
	ds_read_b128 v[66:69], v0 offset:6656
	ds_read_b128 v[164:167], v0 offset:32
	ds_read_b128 v[168:171], v0 offset:6688
	ds_read2_b64 v[238:241], v242 offset0:0 offset1:2
	ds_read2_b64 v[234:237], v163 offset0:32 offset1:34
	ds_read_b128 v[172:175], v0 offset:64
	ds_read_b128 v[176:179], v0 offset:6720
	ds_read_b128 v[180:183], v0 offset:96
	ds_read_b128 v[184:187], v0 offset:6752
	ds_read_b128 v[188:191], v0 offset:128
	ds_read_b128 v[192:195], v0 offset:6784
	ds_read_b128 v[196:199], v0 offset:160
	ds_read_b128 v[220:223], v0 offset:6816
	v_exp_f32_e32 v82, v82
	v_exp_f32_e32 v83, v83
	v_exp_f32_e32 v84, v84
	v_exp_f32_e32 v85, v85
	v_exp_f32_e32 v86, v86
	v_exp_f32_e32 v87, v87
	v_exp_f32_e32 v88, v88
	v_exp_f32_e32 v89, v89
	s_waitcnt lgkmcnt(13)
	v_mfma_f32_32x32x16_bf16 v[50:65], v[50:53], v[122:125], 0
	v_cvt_pk_bf16_f32 v224, v82, v83
	v_cvt_pk_bf16_f32 v225, v84, v85
	v_cvt_pk_bf16_f32 v226, v86, v87
	v_cvt_pk_bf16_f32 v227, v88, v89
	v_exp_f32_e32 v90, v90
	v_add_f32_e32 v200, v82, v83
	s_waitcnt lgkmcnt(12)
	v_mfma_f32_32x32x16_bf16 v[66:81], v[66:69], v[122:125], 0
	v_exp_f32_e32 v91, v91
	v_exp_f32_e32 v92, v92
	v_add_f32_e32 v201, v84, v85
	v_exp_f32_e32 v93, v93
	s_waitcnt lgkmcnt(11)
	v_mfma_f32_32x32x16_bf16 v[50:65], v[164:167], v[126:129], v[50:65]
	v_exp_f32_e32 v94, v94
	v_add_f32_e32 v200, v200, v86
	v_exp_f32_e32 v95, v95
	v_add_f32_e32 v201, v201, v87
	v_exp_f32_e32 v96, v96
	s_waitcnt lgkmcnt(10)
	v_mfma_f32_32x32x16_bf16 v[66:81], v[168:171], v[126:129], v[66:81]
	ds_read2_b64 v[164:167], v242 offset0:4 offset1:6
	ds_read2_b64 v[168:171], v163 offset0:36 offset1:38
	v_add_f32_e32 v200, v200, v88
	v_exp_f32_e32 v97, v97
	v_add_f32_e32 v201, v201, v89
	v_cvt_pk_bf16_f32 v228, v90, v91
	v_cvt_pk_bf16_f32 v229, v92, v93
	s_waitcnt lgkmcnt(11)
	v_mfma_f32_32x32x16_bf16 v[18:33], v[238:241], v[224:227], v[18:33]
	v_cvt_pk_bf16_f32 v230, v94, v95
	v_cvt_pk_bf16_f32 v231, v96, v97
	v_exp_f32_e32 v98, v98
	v_add_f32_e32 v200, v200, v90
	v_exp_f32_e32 v99, v99
	v_add_f32_e32 v201, v201, v91
	s_waitcnt lgkmcnt(10)
	v_mfma_f32_32x32x16_bf16 v[34:49], v[234:237], v[224:227], v[34:49]
	v_exp_f32_e32 v100, v100
	v_add_f32_e32 v200, v200, v92
	v_exp_f32_e32 v101, v101
	v_add_f32_e32 v201, v201, v93
	v_exp_f32_e32 v102, v102
	s_waitcnt lgkmcnt(9)
	v_mfma_f32_32x32x16_bf16 v[50:65], v[172:175], v[134:137], v[50:65]
	v_add_f32_e32 v200, v200, v94
	v_exp_f32_e32 v103, v103
	v_add_f32_e32 v201, v201, v95
	v_exp_f32_e32 v104, v104
	v_add_f32_e32 v200, v200, v96
	s_waitcnt lgkmcnt(8)
	v_mfma_f32_32x32x16_bf16 v[66:81], v[176:179], v[134:137], v[66:81]
	ds_read2_b64 v[172:175], v242 offset0:8 offset1:10
	ds_read2_b64 v[176:179], v163 offset0:40 offset1:42
	v_exp_f32_e32 v105, v105
	v_add_f32_e32 v201, v201, v97
	v_cvt_pk_bf16_f32 v224, v98, v99
	v_cvt_pk_bf16_f32 v225, v100, v101
	v_cvt_pk_bf16_f32 v226, v102, v103
	s_waitcnt lgkmcnt(3)
	v_mfma_f32_32x32x16_bf16 v[18:33], v[164:167], v[228:231], v[18:33]
	v_cvt_pk_bf16_f32 v227, v104, v105
	v_exp_f32_e32 v106, v106
	v_add_f32_e32 v200, v200, v98
	v_exp_f32_e32 v107, v107
	v_add_f32_e32 v201, v201, v99
	s_waitcnt lgkmcnt(2)
	v_mfma_f32_32x32x16_bf16 v[34:49], v[168:171], v[228:231], v[34:49]
	v_exp_f32_e32 v108, v108
	v_add_f32_e32 v200, v200, v100
	v_exp_f32_e32 v109, v109
	v_add_f32_e32 v201, v201, v101
	v_exp_f32_e32 v110, v110
	s_waitcnt lgkmcnt(9)
	v_mfma_f32_32x32x16_bf16 v[50:65], v[180:183], v[138:141], v[50:65]
	v_add_f32_e32 v200, v200, v102
	v_exp_f32_e32 v111, v111
	v_add_f32_e32 v201, v201, v103
	v_exp_f32_e32 v112, v112
	v_add_f32_e32 v200, v200, v104
	s_waitcnt lgkmcnt(8)
	v_mfma_f32_32x32x16_bf16 v[66:81], v[184:187], v[138:141], v[66:81]
	ds_read2_b64 v[180:183], v242 offset0:12 offset1:14
	ds_read2_b64 v[184:187], v163 offset0:44 offset1:46
	v_exp_f32_e32 v113, v113
	v_add_f32_e32 v201, v201, v105
	v_cvt_pk_bf16_f32 v228, v106, v107
	v_cvt_pk_bf16_f32 v229, v108, v109
	v_cvt_pk_bf16_f32 v230, v110, v111
	s_waitcnt lgkmcnt(3)
	v_mfma_f32_32x32x16_bf16 v[18:33], v[172:175], v[224:227], v[18:33]
	v_cvt_pk_bf16_f32 v231, v112, v113
	v_add_f32_e32 v200, v200, v106
	v_add_f32_e32 v201, v201, v107
	v_add_f32_e32 v200, v200, v108
	v_add_f32_e32 v201, v201, v109
	v_add_f32_e32 v200, v200, v110
	v_add_f32_e32 v201, v201, v111
	v_add_f32_e32 v200, v200, v112
	s_waitcnt lgkmcnt(2)
	v_mfma_f32_32x32x16_bf16 v[34:49], v[176:179], v[224:227], v[34:49]
	v_add_f32_e32 v201, v201, v113
	v_add_f32_e32 v200, v200, v201
	v_add_f32_e32 v162, v162, v200
	s_waitcnt lgkmcnt(9)
	v_mfma_f32_32x32x16_bf16 v[50:65], v[188:191], v[142:145], v[50:65]
	s_waitcnt lgkmcnt(0)
	s_and_b64 vcc, exec, s[44:45]
	s_cbranch_vccnz .Lt2a_mid
	s_and_b32 s44, s60, 3
	s_mulk_i32 s44, 0x3400
	s_add_i32 s52, s44, 0
	v_add_u32_e32 v0, s52, v151
	s_waitcnt vmcnt(0)
	ds_write_b128 v0, v[2:5]
	s_and_saveexec_b64 s[44:45], s[40:41]
	v_add_u32_e32 v0, s52, v159
	ds_write_b128 v0, v[10:13]
	s_or_b64 exec, exec, s[44:45]

.Lt2a_end:
	v_mfma_f32_32x32x16_bf16 v[66:81], v[192:195], v[142:145], v[66:81]
	v_mfma_f32_32x32x16_bf16 v[50:65], v[196:199], v[146:149], v[50:65]
	v_mfma_f32_32x32x16_bf16 v[66:81], v[220:223], v[146:149], v[66:81]
	v_mfma_f32_32x32x16_bf16 v[18:33], v[180:183], v[228:231], v[18:33]
	v_mfma_f32_32x32x16_bf16 v[34:49], v[184:187], v[228:231], v[34:49]
	s_branch .LBB0_571
